# self-attn FIXM seam: next-item K/V prefetch issued after last-step barrier, Q prefetch after last gate wait (spread instead of 12-load burst)
# baseline (speedup 1.0000x reference)
.LBB0_896:
	s_andn2_saveexec_b64 s[44:45], s[44:45]
	s_cbranch_execz .LBB0_876
	v_mov_b32_e32 v129, v250
	s_waitcnt lgkmcnt(0)
	s_barrier
	v_readlane_b32 s9, v254, 52
	v_lshlrev_b32_e32 v2, 4, v129
	v_lshlrev_b32_e32 v3, 1, v129
	v_lshrrev_b32_e32 v131, 1, v129
	v_lshlrev_b32_e32 v0, 3, v129
	v_xor_b32_e32 v4, v2, v129
	v_and_b32_e32 v2, 19, v129
	v_and_b32_e32 v3, 8, v3
	v_and_b32_e32 v5, 4, v131
	v_ashrrev_i32_e32 v128, 3, v129
	v_and_b32_e32 v130, 56, v0
	v_or3_b32 v5, v3, v2, v5
	v_mov_b64_e32 v[2:3], s[40:41]
	v_mad_i64_i32 v[0:1], s[2:3], v128, s21, 0
	v_lshlrev_b32_e32 v176, 1, v130
	v_mad_i64_i32 v[2:3], s[2:3], v128, s33, v[2:3]
	v_lshl_add_u64 v[132:133], v[2:3], 0, v[176:177]
	v_lshlrev_b32_e32 v2, 7, v128
	s_movk_i32 s2, 0x70
	v_and_or_b32 v142, v4, s2, v2
	s_mov_b32 s2, 0xd8000
	v_lshl_add_u64 v[0:1], v[0:1], 1, s[42:43]
	v_add_co_u32_e32 v2, vcc, s2, v132
	v_lshl_add_u64 v[0:1], v[0:1], 0, v[176:177]
	v_lshrrev_b32_e32 v40, 1, v5
	v_bfe_u32 v138, v129, 5, 1
	s_waitcnt vmcnt(8)
	ds_write_b128 v142, v[64:67] offset:16384
	ds_write_b128 v142, v[68:71] offset:24576
	ds_write_b128 v142, v[72:75]
	ds_write_b128 v142, v[76:79] offset:8192
	v_addc_co_u32_e32 v3, vcc, 0, v133, vcc
	global_load_dwordx4 v[112:115], v[2:3], off offset:2048
	global_load_dwordx4 v[116:119], v[0:1], off offset:128
	v_bitop3_b32 v0, v40, v138, 7 bitop3:0x6c
	v_lshlrev_b32_e32 v143, 7, v5
	v_lshlrev_b32_e32 v145, 4, v0
	s_waitcnt lgkmcnt(0)
	s_barrier
	v_or_b32_e32 v41, v143, v145
	ds_read_b128 v[0:3], v41 offset:16384
	ds_read_b128 v[4:7], v41 offset:20480
	s_waitcnt lgkmcnt(0)
	s_waitcnt vmcnt(4)
	v_mfma_f32_32x32x16_bf16 v[16:31], v[0:3], v[96:99], 0
	v_or_b32_e32 v32, 2, v138
	v_bitop3_b32 v32, v40, v32, 7 bitop3:0x6c
	v_lshlrev_b32_e32 v146, 4, v32
	v_or_b32_e32 v42, v143, v146
	ds_read_b128 v[32:35], v42 offset:16384
	ds_read_b128 v[36:39], v42 offset:20480
	v_lshrrev_b32_e32 v73, 5, v129
	v_bfe_u32 v74, v129, 1, 3
	v_mfma_f32_32x32x16_bf16 v[0:15], v[4:7], v[96:99], 0
	s_lshr_b32 s2, s21, 6
	v_mad_i64_i32 v[134:135], s[18:19], v128, s33, 0
	s_add_i32 s2, s2, -1
	v_and_b32_e32 v148, 31, v129
	v_lshlrev_b32_e32 v75, 7, v148
	s_mov_b32 s3, 5
	s_waitcnt lgkmcnt(1)
	v_mfma_f32_32x32x16_bf16 v[16:31], v[32:35], v[100:103], v[16:31]
	v_or_b32_e32 v32, 4, v138
	v_bitop3_b32 v32, v40, v32, 7 bitop3:0x6c
	v_lshlrev_b32_e32 v147, 4, v32
	v_or_b32_e32 v43, v143, v147
	s_waitcnt lgkmcnt(0)
	v_mfma_f32_32x32x16_bf16 v[0:15], v[36:39], v[100:103], v[0:15]
	ds_read_b128 v[32:35], v43 offset:16384
	ds_read_b128 v[36:39], v43 offset:20480
	s_waitcnt lgkmcnt(1)
	v_mfma_f32_32x32x16_bf16 v[16:31], v[32:35], v[104:107], v[16:31]
	v_or_b32_e32 v32, 6, v138
	v_bitop3_b32 v32, v40, v32, 7 bitop3:0x6c
	v_lshlrev_b32_e32 v149, 4, v32
	v_or_b32_e32 v72, v143, v149
	ds_read_b128 v[32:35], v72 offset:16384
	s_waitcnt lgkmcnt(1)
	v_mfma_f32_32x32x16_bf16 v[0:15], v[36:39], v[104:107], v[0:15]
	ds_read_b128 v[36:39], v72 offset:20480
	s_waitcnt lgkmcnt(1)
	v_mfma_f32_32x32x16_bf16 v[16:31], v[32:35], v[108:111], v[16:31]
	s_waitcnt lgkmcnt(0)
	v_mfma_f32_32x32x16_bf16 v[0:15], v[36:39], v[108:111], v[0:15]
	s_nop 9
	v_exp_f32_e32 v32, v16
	v_exp_f32_e32 v33, v17
	v_exp_f32_e32 v34, v18
	v_exp_f32_e32 v35, v19
	v_exp_f32_e32 v37, v20
	v_exp_f32_e32 v38, v21
	v_add_f32_e32 v16, 0, v32
	v_add_f32_e32 v17, 0, v33
	v_add_f32_e32 v36, 0, v34
	v_add_f32_e32 v39, 0, v35
	v_add_f32_e32 v40, v37, v16
	v_add_f32_e32 v44, v38, v17
	v_exp_f32_e32 v45, v22
	v_exp_f32_e32 v46, v23
	ds_read_b128 v[16:19], v41 offset:24576
	ds_read_b128 v[20:23], v41 offset:28672
	s_waitcnt lgkmcnt(1)
	v_mfma_f32_32x32x16_bf16 v[48:63], v[16:19], v[96:99], 0
	v_exp_f32_e32 v41, v24
	v_add_f32_e32 v36, v45, v36
	v_add_f32_e32 v39, v46, v39
	ds_read_b128 v[64:67], v42 offset:24576
	ds_read_b128 v[68:71], v42 offset:28672
	v_exp_f32_e32 v42, v25
	v_add_f32_e32 v24, v41, v40
	v_exp_f32_e32 v40, v26
	v_exp_f32_e32 v47, v27
	v_exp_f32_e32 v28, v28
	v_exp_f32_e32 v29, v29
	v_exp_f32_e32 v30, v30
	v_exp_f32_e32 v31, v31
	v_exp_f32_e32 v77, v0
	v_exp_f32_e32 v78, v1
	v_add_f32_e32 v25, v42, v44
	s_waitcnt lgkmcnt(1)
	v_mfma_f32_32x32x16_bf16 v[48:63], v[64:67], v[100:103], v[48:63]
	v_add_f32_e32 v26, v40, v36
	v_add_f32_e32 v27, v47, v39
	v_cvt_pk_bf16_f32 v80, v32, v33
	v_cvt_pk_bf16_f32 v81, v34, v35
	v_cvt_pk_bf16_f32 v82, v37, v38
	v_cvt_pk_bf16_f32 v83, v45, v46
	v_add_f32_e32 v24, v28, v24
	v_add_f32_e32 v25, v29, v25
	v_exp_f32_e32 v4, v4
	v_add_f32_e32 v76, v30, v26
	v_add_f32_e32 v0, v31, v27
	v_add_f32_e32 v79, v77, v24
	v_add_f32_e32 v88, v78, v25
	ds_read_b128 v[16:19], v43 offset:24576
	ds_read_b128 v[24:27], v43 offset:28672
	v_cvt_pk_bf16_f32 v86, v28, v29
	v_exp_f32_e32 v28, v2
	v_exp_f32_e32 v29, v3
	v_exp_f32_e32 v5, v5
	s_waitcnt lgkmcnt(1)
	v_mfma_f32_32x32x16_bf16 v[48:63], v[16:19], v[104:107], v[48:63]
	v_cvt_pk_bf16_f32 v84, v41, v42
	v_cvt_pk_bf16_f32 v85, v40, v47
	v_exp_f32_e32 v6, v6
	v_exp_f32_e32 v7, v7
	v_cvt_pk_bf16_f32 v87, v30, v31
	v_add_f32_e32 v30, v28, v76
	v_add_f32_e32 v31, v29, v0
	v_mfma_f32_32x32x16_bf16 v[32:47], v[20:23], v[96:99], 0
	ds_read_b128 v[0:3], v72 offset:24576
	ds_read_b128 v[20:23], v72 offset:28672
	v_add_f32_e32 v64, v4, v79
	v_add_f32_e32 v65, v5, v88
	v_add_f32_e32 v30, v6, v30
	v_exp_f32_e32 v8, v8
	v_exp_f32_e32 v9, v9
	v_add_f32_e32 v31, v7, v31
	v_cvt_pk_bf16_f32 v90, v4, v5
	v_exp_f32_e32 v4, v10
	v_exp_f32_e32 v5, v11
	v_exp_f32_e32 v11, v13
	v_cvt_pk_bf16_f32 v91, v6, v7
	v_exp_f32_e32 v7, v12
	s_waitcnt lgkmcnt(1)
	v_mfma_f32_32x32x16_bf16 v[48:63], v[0:3], v[108:111], v[48:63]
	v_exp_f32_e32 v0, v14
	v_exp_f32_e32 v1, v15
	v_add_f32_e32 v64, v8, v64
	v_add_f32_e32 v65, v9, v65
	v_cvt_pk_bf16_f32 v88, v77, v78
	v_cvt_pk_bf16_f32 v89, v28, v29
	v_add_f32_e32 v6, v4, v30
	v_mfma_f32_32x32x16_bf16 v[32:47], v[68:71], v[100:103], v[32:47]
	v_add_f32_e32 v10, v5, v31
	v_mov_b32_e32 v16, 0
	v_add_f32_e32 v12, v7, v64
	v_add_f32_e32 v2, v11, v65
	v_add_f32_e32 v3, v0, v6
	v_add_f32_e32 v6, v1, v10
	v_mfma_f32_32x32x16_bf16 v[32:47], v[24:27], v[104:107], v[32:47]
	v_cvt_pk_bf16_f32 v95, v0, v1
	v_add_f32_e32 v0, v12, v2
	v_add_f32_e32 v1, v3, v6
	v_add_f32_e32 v0, v0, v1
	v_add_f32_e32 v150, 0, v0
	v_bitop3_b32 v0, v73, v74, 1 bitop3:0x6c
	v_lshlrev_b32_e32 v2, 4, v0
	v_bitop3_b32 v0, v138, v74, 2 bitop3:0x36
	v_lshlrev_b32_e32 v3, 4, v0
	v_bitop3_b32 v0, v138, v74, 4 bitop3:0x36
	v_cvt_pk_bf16_f32 v93, v4, v5
	v_lshlrev_b32_e32 v4, 4, v0
	v_bitop3_b32 v0, v138, v74, 6 bitop3:0x36
	v_lshlrev_b32_e32 v5, 4, v0
	v_and_b32_e32 v0, 7, v129
	v_cvt_pk_bf16_f32 v92, v8, v9
	v_cvt_pk_bf16_f32 v94, v7, v11
	v_lshlrev_b32_e32 v176, 4, v0
	v_lshlrev_b32_e32 v0, 1, v128
	s_waitcnt lgkmcnt(0)
	s_barrier
	v_mad_i64_i32 v[0:1], s[18:19], v0, s21, v[176:177]
	s_add_u32 s18, s9, s38
	v_readlane_b32 s9, v254, 53
	s_addc_u32 s19, s9, s39
	s_waitcnt lgkmcnt(0)
	v_mfma_f32_32x32x16_bf16 v[32:47], v[20:23], v[108:111], v[32:47]
	v_lshl_add_u64 v[136:137], s[18:19], 0, v[0:1]
	v_add_u32_e32 v144, v75, v2
	v_add_u32_e32 v141, v75, v3
	v_add_u32_e32 v140, v75, v4
	v_add_u32_e32 v139, v75, v5
	v_mov_b32_e32 v17, v16
	v_mov_b32_e32 v18, v16
	v_mov_b32_e32 v19, v16
	v_mov_b32_e32 v20, v16
	v_mov_b32_e32 v21, v16
	v_mov_b32_e32 v22, v16
	v_mov_b32_e32 v23, v16
	v_mov_b32_e32 v24, v16
	v_mov_b32_e32 v25, v16
	v_mov_b32_e32 v26, v16
	v_mov_b32_e32 v27, v16
	v_mov_b32_e32 v28, v16
	v_mov_b32_e32 v29, v16
	v_mov_b32_e32 v30, v16
	v_mov_b32_e32 v31, v16
	v_mov_b32_e32 v0, v16
	v_mov_b32_e32 v1, v16
	v_mov_b32_e32 v2, v16
	v_mov_b32_e32 v3, v16
	v_mov_b32_e32 v4, v16
	v_mov_b32_e32 v5, v16
	v_mov_b32_e32 v6, v16
	v_mov_b32_e32 v7, v16
	v_mov_b32_e32 v8, v16
	v_mov_b32_e32 v9, v16
	v_mov_b32_e32 v10, v16
	v_mov_b32_e32 v11, v16
	v_mov_b32_e32 v12, v16
	v_mov_b32_e32 v13, v16
	v_mov_b32_e32 v14, v16
	v_mov_b32_e32 v15, v16
.LBB0_898:
	s_add_i32 s9, s3, -1
	s_min_u32 s9, s9, s2
	s_lshl_b32 s9, s9, 6
	s_waitcnt vmcnt(1)
	ds_write_b128 v142, v[112:115] offset:16384
	s_waitcnt vmcnt(0)
	ds_write_b128 v142, v[116:119] offset:24576
	v_mad_u64_u32 v[64:65], s[18:19], s9, v237, v[132:133]
	global_load_dwordx4 v[120:123], v[64:65], off offset:2048
	global_load_dwordx4 v[124:127], v[136:137], off offset:-128
	ds_read_b128 v[64:67], v144 offset:8192
	ds_read_b128 v[68:71], v144 offset:12288
	ds_read_b128 v[72:75], v141 offset:8192
	ds_read_b128 v[76:79], v141 offset:12288
	v_exp_f32_e32 v151, v48
	v_exp_f32_e32 v152, v49
	s_waitcnt lgkmcnt(3)
	v_mfma_f32_32x32x16_bf16 v[16:31], v[64:67], v[80:83], v[16:31]
	v_exp_f32_e32 v153, v50
	v_add_f32_e32 v112, 0, v151
	v_add_f32_e32 v113, 0, v152
	v_exp_f32_e32 v154, v51
	ds_read_b128 v[48:51], v140 offset:8192
	ds_read_b128 v[64:67], v140 offset:12288
	v_exp_f32_e32 v155, v52
	s_waitcnt lgkmcnt(4)
	v_mfma_f32_32x32x16_bf16 v[0:15], v[68:71], v[80:83], v[0:15]
	v_exp_f32_e32 v156, v53
	v_exp_f32_e32 v159, v54
	v_exp_f32_e32 v160, v55
	v_add_f32_e32 v114, 0, v153
	v_add_f32_e32 v115, 0, v154
	v_exp_f32_e32 v162, v57
	s_waitcnt lgkmcnt(3)
	v_mfma_f32_32x32x16_bf16 v[16:31], v[72:75], v[84:87], v[16:31]
	ds_read_b128 v[68:71], v139 offset:8192
	ds_read_b128 v[80:83], v139 offset:12288
	v_add_f32_e32 v157, v155, v112
	v_add_f32_e32 v158, v156, v113
	v_add_u32_e32 v164, v143, v145
	ds_read_b128 v[52:55], v164
	ds_read_b128 v[72:75], v164 offset:4096
	v_add_f32_e32 v161, v159, v114
	s_waitcnt lgkmcnt(6)
	v_mfma_f32_32x32x16_bf16 v[0:15], v[76:79], v[84:87], v[0:15]
	v_exp_f32_e32 v77, v56
	v_add_f32_e32 v76, v160, v115
	v_exp_f32_e32 v62, v62
	v_add_u32_e32 v165, v143, v146
	ds_read_b128 v[112:115], v165
	ds_read_b128 v[116:119], v165 offset:4096
	v_cvt_pk_bf16_f32 v56, v151, v152
	s_waitcnt lgkmcnt(7)
	v_mfma_f32_32x32x16_bf16 v[16:31], v[48:51], v[88:91], v[16:31]
	v_exp_f32_e32 v49, v58
	v_exp_f32_e32 v50, v59
	v_add_f32_e32 v48, v77, v157
	v_add_f32_e32 v51, v162, v158
	v_add_f32_e32 v78, v49, v161
	v_add_f32_e32 v76, v50, v76
	s_waitcnt lgkmcnt(6)
	v_mfma_f32_32x32x16_bf16 v[0:15], v[64:67], v[88:91], v[0:15]
	v_exp_f32_e32 v60, v60
	v_add_f32_e32 v151, v62, v78
	v_exp_f32_e32 v61, v61
	v_exp_f32_e32 v63, v63
	v_cvt_pk_bf16_f32 v59, v159, v160
	v_exp_f32_e32 v160, v33
	s_waitcnt lgkmcnt(5)
	v_mfma_f32_32x32x16_bf16 v[16:31], v[68:71], v[92:95], v[16:31]
	v_cvt_pk_bf16_f32 v57, v153, v154
	v_cvt_pk_bf16_f32 v58, v155, v156
	v_add_f32_e32 v48, v60, v48
	v_add_f32_e32 v51, v61, v51
	v_cvt_pk_bf16_f32 v49, v49, v50
	s_waitcnt lgkmcnt(4)
	v_mfma_f32_32x32x16_bf16 v[0:15], v[80:83], v[92:95], v[0:15]
	v_exp_f32_e32 v95, v32
	v_add_f32_e32 v32, v63, v76
	v_add_f32_e32 v163, v160, v51
	v_add_f32_e32 v161, v95, v48
	v_cvt_pk_bf16_f32 v48, v77, v162
	v_cvt_pk_bf16_f32 v51, v62, v63
	s_waitcnt lgkmcnt(3)
	v_mfma_f32_32x32x16_bf16 v[78:93], v[52:55], v[96:99], 0
	v_cvt_pk_bf16_f32 v50, v60, v61
	v_exp_f32_e32 v60, v34
	v_exp_f32_e32 v61, v35
	v_exp_f32_e32 v36, v36
	v_exp_f32_e32 v37, v37
	v_exp_f32_e32 v38, v38
	v_exp_f32_e32 v39, v39
	s_waitcnt lgkmcnt(2)
	v_mfma_f32_32x32x16_bf16 v[62:77], v[72:75], v[96:99], 0
	v_add_u32_e32 v166, v143, v147
	ds_read_b128 v[52:55], v166
	ds_read_b128 v[152:155], v166 offset:4096
	v_add_f32_e32 v151, v60, v151
	v_add_f32_e32 v162, v61, v32
	s_waitcnt lgkmcnt(3)
	v_mfma_f32_32x32x16_bf16 v[78:93], v[112:115], v[100:103], v[78:93]
	v_add_u32_e32 v94, v143, v149
	v_add_f32_e32 v112, v36, v161
	v_add_f32_e32 v113, v37, v163
	v_add_f32_e32 v114, v38, v151
	v_exp_f32_e32 v115, v40
	v_add_f32_e32 v40, v39, v162
	ds_read_b128 v[32:35], v94
	ds_read_b128 v[156:159], v94 offset:4096
	s_waitcnt lgkmcnt(4)
	v_mfma_f32_32x32x16_bf16 v[62:77], v[116:119], v[100:103], v[62:77]
	v_exp_f32_e32 v116, v41
	v_add_f32_e32 v41, v115, v112
	s_min_u32 s9, s3, s2
	s_lshl_b32 s9, s9, 6
	v_add_f32_e32 v112, v116, v113
	s_waitcnt lgkmcnt(3)
	v_mfma_f32_32x32x16_bf16 v[78:93], v[52:55], v[104:107], v[78:93]
	v_cvt_pk_bf16_f32 v54, v36, v37
	v_exp_f32_e32 v37, v42
	v_cvt_pk_bf16_f32 v55, v38, v39
	v_exp_f32_e32 v38, v43
	v_exp_f32_e32 v39, v44
	v_exp_f32_e32 v44, v45
	v_exp_f32_e32 v45, v46
	v_exp_f32_e32 v46, v47
	v_cvt_pk_bf16_f32 v52, v95, v160
	v_cvt_pk_bf16_f32 v53, v60, v61
	v_add_f32_e32 v36, v37, v114
	v_add_f32_e32 v43, v38, v40
	v_add_f32_e32 v40, v39, v41
	v_add_f32_e32 v42, v44, v112
	v_add_f32_e32 v41, v45, v36
	v_add_f32_e32 v43, v46, v43
	v_cvt_pk_bf16_f32 v36, v115, v116
	v_cvt_pk_bf16_f32 v37, v37, v38
	v_cvt_pk_bf16_f32 v38, v39, v44
	v_cvt_pk_bf16_f32 v39, v45, v46
	s_waitcnt lgkmcnt(1)
	v_mfma_f32_32x32x16_bf16 v[78:93], v[32:35], v[108:111], v[78:93]
	s_waitcnt lgkmcnt(0)
	s_barrier
	v_mad_u64_u32 v[32:33], s[18:19], s9, v237, v[132:133]
	global_load_dwordx4 v[112:115], v[32:33], off offset:2048
	global_load_dwordx4 v[116:119], v[136:137], off
	v_add_f32_e64 v32, v40, v42
	v_add_f32_e64 v33, v41, v43
	s_waitcnt vmcnt(3)
	ds_write_b128 v142, v[120:123]
	s_waitcnt vmcnt(2)
	ds_write_b128 v142, v[124:127] offset:8192
	v_mfma_f32_32x32x16_bf16 v[62:77], v[152:155], v[104:107], v[62:77]
	v_add_f32_e32 v32, v32, v33
	v_add_f32_e32 v150, v150, v32
	s_waitcnt lgkmcnt(2)
	v_mfma_f32_32x32x16_bf16 v[62:77], v[156:159], v[108:111], v[62:77]
	ds_read_b128 v[32:35], v144 offset:24576
	ds_read_b128 v[40:43], v144 offset:28672
	ds_read_b128 v[44:47], v141 offset:24576
	ds_read_b128 v[120:123], v141 offset:28672
	v_exp_f32_e32 v60, v78
	s_waitcnt lgkmcnt(3)
	v_mfma_f32_32x32x16_bf16 v[16:31], v[32:35], v[56:59], v[16:31]
	v_exp_f32_e32 v61, v79
	v_exp_f32_e32 v95, v80
	v_add_f32_e32 v78, 0, v60
	v_exp_f32_e32 v81, v81
	v_add_f32_e32 v79, 0, v61
	ds_read_b128 v[152:155], v140 offset:24576
	ds_read_b128 v[156:159], v140 offset:28672
	s_waitcnt lgkmcnt(4)
	v_mfma_f32_32x32x16_bf16 v[0:15], v[40:43], v[56:59], v[0:15]
	v_exp_f32_e32 v82, v82
	v_exp_f32_e32 v83, v83
	v_add_f32_e32 v80, 0, v95
	v_add_f32_e32 v124, 0, v81
	v_add_f32_e32 v78, v82, v78
	v_add_f32_e32 v79, v83, v79
	s_waitcnt lgkmcnt(2)
	v_mfma_f32_32x32x16_bf16 v[0:15], v[120:123], v[48:51], v[0:15]
	ds_read_b128 v[56:59], v139 offset:24576
	ds_read_b128 v[160:163], v139 offset:28672
	ds_read_b128 v[40:43], v164 offset:16384
	ds_read_b128 v[32:35], v164 offset:20480
	v_cvt_pk_bf16_f32 v82, v82, v83
	v_exp_f32_e32 v151, v62
	v_exp_f32_e32 v64, v64
	v_exp_f32_e32 v65, v65
	v_mfma_f32_32x32x16_bf16 v[16:31], v[44:47], v[48:51], v[16:31]
	v_exp_f32_e32 v44, v84
	v_exp_f32_e32 v45, v85
	v_exp_f32_e32 v84, v86
	v_exp_f32_e32 v85, v87
	v_add_f32_e32 v46, v44, v80
	v_add_f32_e32 v47, v45, v124
	v_add_f32_e32 v48, v84, v78
	s_waitcnt lgkmcnt(4)
	v_mfma_f32_32x32x16_bf16 v[0:15], v[156:159], v[52:55], v[0:15]
	v_add_f32_e32 v49, v85, v79
	v_exp_f32_e32 v78, v88
	v_exp_f32_e32 v79, v89
	v_exp_f32_e32 v87, v92
	v_cvt_pk_bf16_f32 v83, v44, v45
	v_exp_f32_e32 v44, v90
	v_mfma_f32_32x32x16_bf16 v[16:31], v[152:155], v[52:55], v[16:31]
	v_exp_f32_e32 v45, v91
	v_exp_f32_e32 v92, v93
	v_add_f32_e32 v46, v78, v46
	v_add_f32_e32 v47, v79, v47
	ds_read_b128 v[124:127], v165 offset:16384
	ds_read_b128 v[120:123], v165 offset:20480
	s_waitcnt lgkmcnt(4)
	v_mfma_f32_32x32x16_bf16 v[0:15], v[160:163], v[36:39], v[0:15]
	v_exp_f32_e32 v160, v63
	v_cvt_pk_bf16_f32 v80, v60, v61
	v_cvt_pk_bf16_f32 v81, v95, v81
	v_add_f32_e32 v48, v44, v48
	v_add_f32_e32 v49, v45, v49
	v_add_f32_e32 v46, v87, v46
	v_add_f32_e32 v47, v92, v47
	v_mfma_f32_32x32x16_bf16 v[16:31], v[56:59], v[36:39], v[16:31]
	v_add_f32_e32 v161, v151, v48
	v_add_f32_e32 v162, v160, v49
	v_cvt_pk_bf16_f32 v84, v84, v85
	v_cvt_pk_bf16_f32 v85, v78, v79
	v_cvt_pk_bf16_f32 v86, v44, v45
	v_add_f32_e32 v78, v64, v46
	v_add_f32_e32 v79, v65, v47
	s_waitcnt lgkmcnt(3)
	v_mfma_f32_32x32x16_bf16 v[48:63], v[40:43], v[96:99], 0
	ds_read_b128 v[88:91], v166 offset:16384
	ds_read_b128 v[152:155], v166 offset:20480
	v_exp_f32_e32 v66, v66
	v_exp_f32_e32 v67, v67
	v_exp_f32_e32 v68, v68
	v_exp_f32_e32 v69, v69
	v_cvt_pk_bf16_f32 v87, v87, v92
	s_waitcnt lgkmcnt(4)
	v_mfma_f32_32x32x16_bf16 v[32:47], v[32:35], v[96:99], 0
	ds_read_b128 v[156:159], v94 offset:16384
	ds_read_b128 v[92:95], v94 offset:20480
	v_add_f32_e32 v161, v66, v161
	v_add_f32_e32 v162, v67, v162
	v_add_f32_e32 v78, v68, v78
	v_add_f32_e32 v79, v69, v79
	s_waitcnt lgkmcnt(5)
	v_mfma_f32_32x32x16_bf16 v[48:63], v[124:127], v[100:103], v[48:63]
	v_exp_f32_e32 v70, v70
	v_exp_f32_e32 v71, v71
	s_add_i32 s9, s3, 2
	s_add_i32 s3, s3, -2
	v_lshl_add_u64 v[136:137], v[136:137], 0, s[22:23]
	s_waitcnt lgkmcnt(4)
	v_mfma_f32_32x32x16_bf16 v[32:47], v[120:123], v[100:103], v[32:47]
	v_add_f32_e32 v120, v70, v161
	v_add_f32_e32 v121, v71, v162
	s_cmp_lt_u32 s3, s2
	s_mov_b32 s3, s9
	s_waitcnt lgkmcnt(3)
	v_mfma_f32_32x32x16_bf16 v[48:63], v[88:91], v[104:107], v[48:63]
	v_cvt_pk_bf16_f32 v91, v68, v69
	v_exp_f32_e32 v68, v72
	v_exp_f32_e32 v69, v73
	v_exp_f32_e32 v72, v74
	v_exp_f32_e32 v73, v75
	v_exp_f32_e32 v74, v76
	v_exp_f32_e32 v75, v77
	s_waitcnt lgkmcnt(2)
	v_mfma_f32_32x32x16_bf16 v[32:47], v[152:155], v[104:107], v[32:47]
	v_cvt_pk_bf16_f32 v88, v151, v160
	v_cvt_pk_bf16_f32 v89, v64, v65
	v_cvt_pk_bf16_f32 v90, v66, v67
	v_add_f32_e32 v65, v68, v78
	v_add_f32_e32 v67, v69, v79
	s_waitcnt lgkmcnt(1)
	v_mfma_f32_32x32x16_bf16 v[48:63], v[156:159], v[108:111], v[48:63]
	v_add_f32_e32 v64, v72, v120
	v_add_f32_e32 v66, v73, v121
	v_add_f32_e32 v65, v74, v65
	v_add_f32_e32 v67, v75, v67
	s_waitcnt lgkmcnt(0)
	v_mfma_f32_32x32x16_bf16 v[32:47], v[92:95], v[108:111], v[32:47]
	v_cvt_pk_bf16_f32 v92, v70, v71
	v_cvt_pk_bf16_f32 v93, v68, v69
	v_cvt_pk_bf16_f32 v94, v72, v73
	v_cvt_pk_bf16_f32 v95, v74, v75
	v_add_f32_e64 v64, v64, v66
	v_add_f32_e64 v65, v65, v67
	s_waitcnt lgkmcnt(0)
	s_barrier
	v_add_f32_e32 v64, v64, v65
	v_add_f32_e32 v150, v150, v64
	s_cbranch_scc1 .LBB0_898
	v_ashrrev_i32_e32 v64, 1, v129
	v_and_or_b32 v132, v64, s88, v148
	v_mov_b64_e32 v[64:65], s[12:13]
	v_mad_i64_i32 v[64:65], s[2:3], v132, s33, v[64:65]
	v_lshlrev_b32_e32 v176, 4, v138
	s_waitcnt vmcnt(1)
	ds_write_b128 v142, v[112:115] offset:16384
	s_waitcnt vmcnt(0)
	ds_write_b128 v142, v[116:119] offset:24576
	v_lshl_add_u64 v[64:65], v[64:65], 0, v[176:177]
	global_load_dwordx4 v[124:127], v[64:65], off offset:2560
	global_load_dwordx4 v[120:123], v[64:65], off offset:2592
	global_load_dwordx4 v[116:119], v[64:65], off offset:2624
	global_load_dwordx4 v[112:115], v[64:65], off offset:2656
	v_mov_b64_e32 v[184:185], s[14:15]
	v_mad_i64_i32 v[184:185], s[2:3], v132, s33, v[184:185]
	v_and_b32_e32 v66, 16, v131
	v_mov_b32_e32 v67, v177
	v_lshl_add_u64 v[184:185], v[184:185], 0, v[66:67]
	v_lshl_add_u64 v[64:65], s[34:35], 0, v[134:135]
	v_lshlrev_b32_e32 v76, 1, v130
	v_mov_b32_e32 v77, v177
	v_lshl_add_u64 v[186:187], v[64:65], 0, v[76:77]
	s_mov_b32 s2, 0x48000
	v_add_co_u32_e32 v188, vcc, s2, v186
	s_mov_b32 s2, 0x90000
	s_nop 0
	v_addc_co_u32_e32 v189, vcc, 0, v187, vcc
	v_ashrrev_i32_e32 v133, 31, v132
	v_add_co_u32_e32 v190, vcc, s2, v186
	v_mad_i64_i32 v[78:79], s[2:3], s8, v128, 0
	v_lshl_add_u64 v[78:79], v[78:79], 1, s[10:11]
	v_addc_co_u32_e32 v191, vcc, 0, v187, vcc
	v_lshl_add_u64 v[192:193], v[78:79], 0, v[76:77]
	ds_read_b128 v[128:131], v144 offset:8192
	ds_read_b128 v[134:137], v144 offset:12288
	ds_read_b128 v[146:149], v141 offset:8192
	ds_read_b128 v[152:155], v141 offset:12288
	v_exp_f32_e32 v138, v48
	v_exp_f32_e32 v142, v49
	s_waitcnt lgkmcnt(3)
	v_mfma_f32_32x32x16_bf16 v[16:31], v[128:131], v[80:83], v[16:31]
	v_exp_f32_e32 v151, v50
	v_add_f32_e32 v143, 0, v138
	v_add_f32_e32 v145, 0, v142
	v_exp_f32_e32 v156, v51
	ds_read_b128 v[48:51], v140 offset:8192
	ds_read_b128 v[128:131], v140 offset:12288
	v_exp_f32_e32 v52, v52
	s_waitcnt lgkmcnt(4)
	v_mfma_f32_32x32x16_bf16 v[0:15], v[134:137], v[80:83], v[0:15]
	v_exp_f32_e32 v53, v53
	v_exp_f32_e32 v54, v54
	v_exp_f32_e32 v55, v55
	v_add_f32_e32 v157, 0, v151
	v_add_f32_e32 v158, 0, v156
	v_add_f32_e32 v143, v52, v143
	s_waitcnt lgkmcnt(3)
	v_mfma_f32_32x32x16_bf16 v[16:31], v[146:149], v[84:87], v[16:31]
	v_add_f32_e32 v145, v53, v145
	v_add_f32_e32 v146, v54, v157
	ds_read_b128 v[80:83], v139 offset:8192
	ds_read_b128 v[134:137], v139 offset:12288
	v_exp_f32_e32 v56, v56
	v_exp_f32_e32 v57, v57
	v_exp_f32_e32 v58, v58
	s_waitcnt lgkmcnt(4)
	v_mfma_f32_32x32x16_bf16 v[0:15], v[152:155], v[84:87], v[0:15]
	v_add_f32_e32 v84, v55, v158
	v_exp_f32_e32 v59, v59
	v_exp_f32_e32 v60, v60
	v_exp_f32_e32 v32, v32
	v_exp_f32_e32 v33, v33
	v_exp_f32_e32 v34, v34
	s_waitcnt lgkmcnt(3)
	v_mfma_f32_32x32x16_bf16 v[16:31], v[48:51], v[88:91], v[16:31]
	v_cvt_pk_bf16_f32 v51, v54, v55
	v_exp_f32_e32 v54, v61
	v_exp_f32_e32 v55, v62
	v_exp_f32_e32 v61, v63
	v_exp_f32_e32 v35, v35
	v_add_f32_e32 v85, v56, v143
	v_add_f32_e32 v86, v57, v145
	v_add_f32_e32 v87, v58, v146
	v_add_f32_e32 v84, v59, v84
	v_cvt_pk_bf16_f32 v48, v138, v142
	v_cvt_pk_bf16_f32 v49, v151, v156
	v_cvt_pk_bf16_f32 v50, v52, v53
	v_add_f32_e32 v52, v60, v85
	v_add_f32_e32 v53, v54, v86
	v_add_f32_e32 v62, v55, v87
	v_add_f32_e32 v63, v61, v84
	v_exp_f32_e32 v36, v36
	v_exp_f32_e32 v37, v37
	v_exp_f32_e32 v38, v38
	v_exp_f32_e32 v39, v39
	s_waitcnt lgkmcnt(1)
	v_mfma_f32_32x32x16_bf16 v[16:31], v[80:83], v[92:95], v[16:31]
	v_add_f32_e32 v80, v32, v52
	v_add_f32_e32 v81, v33, v53
	v_cvt_pk_bf16_f32 v52, v56, v57
	v_cvt_pk_bf16_f32 v53, v58, v59
	v_cvt_pk_bf16_f32 v54, v60, v54
	v_cvt_pk_bf16_f32 v55, v55, v61
	v_add_f32_e32 v56, v34, v62
	v_add_f32_e32 v57, v35, v63
	v_exp_f32_e32 v40, v40
	v_add_f32_e32 v58, v36, v80
	v_add_f32_e32 v59, v37, v81
	v_add_f32_e32 v56, v38, v56
	v_exp_f32_e32 v41, v41
	v_add_f32_e32 v57, v39, v57
	v_mfma_f32_32x32x16_bf16 v[0:15], v[128:131], v[88:91], v[0:15]
	v_cvt_pk_bf16_f32 v32, v32, v33
	v_cvt_pk_bf16_f32 v33, v34, v35
	v_cvt_pk_bf16_f32 v34, v36, v37
	v_exp_f32_e32 v37, v42
	v_cvt_pk_bf16_f32 v35, v38, v39
	v_exp_f32_e32 v38, v43
	v_exp_f32_e32 v39, v44
	v_exp_f32_e32 v43, v45
	v_exp_f32_e32 v44, v46
	v_exp_f32_e32 v45, v47
	v_add_f32_e32 v58, v40, v58
	v_add_f32_e32 v59, v41, v59
	v_add_f32_e32 v36, v37, v56
	v_add_f32_e32 v42, v38, v57
	v_add_f32_e32 v56, v39, v58
	v_add_f32_e32 v58, v43, v59
	s_waitcnt lgkmcnt(0)
	v_mfma_f32_32x32x16_bf16 v[0:15], v[134:137], v[92:95], v[0:15]
	v_add_f32_e32 v57, v44, v36
	v_add_f32_e32 v59, v45, v42
	v_cvt_pk_bf16_f32 v36, v40, v41
	v_cvt_pk_bf16_f32 v37, v37, v38
	v_cvt_pk_bf16_f32 v38, v39, v43
	v_cvt_pk_bf16_f32 v39, v44, v45
	s_waitcnt lgkmcnt(0)
	s_barrier
	global_load_dwordx4 v[64:67], v[186:187], off offset:2048
	global_load_dwordx4 v[68:71], v[188:189], off offset:2048
	global_load_dwordx4 v[72:75], v[190:191], off offset:2048
	global_load_dwordx4 v[76:79], v[192:193], off
	ds_read_b128 v[40:43], v144 offset:24576
	ds_read_b128 v[44:47], v144 offset:28672
	s_waitcnt lgkmcnt(1)
	v_mfma_f32_32x32x16_bf16 v[16:31], v[40:43], v[48:51], v[16:31]
	s_waitcnt lgkmcnt(0)
	v_mfma_f32_32x32x16_bf16 v[0:15], v[44:47], v[48:51], v[0:15]
	ds_read_b128 v[40:43], v141 offset:24576
	ds_read_b128 v[44:47], v141 offset:28672
	s_waitcnt lgkmcnt(1)
	v_mfma_f32_32x32x16_bf16 v[16:31], v[40:43], v[52:55], v[16:31]
	s_waitcnt lgkmcnt(0)
	v_mfma_f32_32x32x16_bf16 v[0:15], v[44:47], v[52:55], v[0:15]
	ds_read_b128 v[40:43], v140 offset:24576
	ds_read_b128 v[44:47], v140 offset:28672
	s_waitcnt lgkmcnt(1)
	v_mfma_f32_32x32x16_bf16 v[16:31], v[40:43], v[32:35], v[16:31]
	s_waitcnt lgkmcnt(0)
	v_mfma_f32_32x32x16_bf16 v[0:15], v[44:47], v[32:35], v[0:15]
	ds_read_b128 v[32:35], v139 offset:24576
	ds_read_b128 v[40:43], v139 offset:28672
	s_waitcnt lgkmcnt(1)
	v_mfma_f32_32x32x16_bf16 v[16:31], v[32:35], v[36:39], v[16:31]
	v_add_f32_e64 v32, v56, v58
	v_add_f32_e64 v33, v57, v59
	v_add_f32_e32 v32, v32, v33
	v_add_f32_e32 v32, v150, v32
	v_mov_b32_e32 v33, v32
	s_nop 1
	v_permlane32_swap_b32_e32 v32, v33
	v_add_f32_e32 v32, v32, v33
	v_div_scale_f32 v33, s[2:3], v32, v32, 1.0
	v_rcp_f32_e32 v34, v33
	s_waitcnt lgkmcnt(0)
	v_mfma_f32_32x32x16_bf16 v[0:15], v[40:43], v[36:39], v[0:15]
	s_waitcnt vmcnt(7)
	v_mov_b32_e32 v40, v127
	s_nop 1
	v_permlane32_swap_b32_e32 v125, v40
	v_fma_f32 v35, -v33, v34, 1.0
	v_fmac_f32_e32 v34, v35, v34
	v_div_scale_f32 v35, vcc, 1.0, v32, 1.0
	v_mul_f32_e32 v36, v35, v34
	v_fma_f32 v37, -v33, v36, v35
	v_fmac_f32_e32 v36, v37, v34
	v_fma_f32 v33, -v33, v36, v35
	v_div_fmas_f32 v33, v33, v34, v36
	v_mov_b32_e32 v35, v126
	v_div_fixup_f32 v34, v33, v32, 1.0
	s_nop 0
	v_permlane32_swap_b32_e32 v124, v35
	v_lshlrev_b32_e32 v38, 16, v124
	v_and_b32_e32 v39, 0xffff0000, v124
	v_mul_f32_e32 v16, v16, v34
	v_mul_f32_e32 v17, v17, v34
	v_mul_f32_e32 v18, v18, v34
	v_mul_f32_e32 v19, v19, v34
	v_mul_f32_e32 v16, v16, v38
	v_mul_f32_e32 v17, v17, v39
	v_lshlrev_b32_e32 v38, 16, v125
	v_and_b32_e32 v39, 0xffff0000, v125
	v_mul_f32_e32 v18, v18, v38
	v_mul_f32_e32 v19, v19, v39
	v_cvt_pk_bf16_f32 v16, v16, v17
	v_cvt_pk_bf16_f32 v17, v18, v19
	v_lshlrev_b32_e32 v18, 16, v35
	v_and_b32_e32 v19, 0xffff0000, v35
	v_mul_f32_e32 v20, v20, v34
	v_mul_f32_e32 v21, v21, v34
	v_mul_f32_e32 v22, v22, v34
	v_mul_f32_e32 v23, v23, v34
	v_mul_f32_e32 v18, v20, v18
	v_mul_f32_e32 v19, v21, v19
	v_lshlrev_b32_e32 v20, 16, v40
	v_and_b32_e32 v21, 0xffff0000, v40
	v_lshlrev_b64 v[32:33], 11, v[132:133]
	v_mul_f32_e32 v20, v22, v20
	v_mul_f32_e32 v21, v23, v21
	v_lshl_add_u64 v[32:33], s[6:7], 0, v[32:33]
	v_cvt_pk_bf16_f32 v18, v18, v19
	v_cvt_pk_bf16_f32 v19, v20, v21
	s_waitcnt vmcnt(6)
	v_mov_b32_e32 v22, v122
	v_lshl_add_u64 v[36:37], v[32:33], 0, v[176:177]
	v_permlane32_swap_b32_e32 v16, v18
	v_permlane32_swap_b32_e32 v17, v19
	v_permlane32_swap_b32_e32 v120, v22
	v_mov_b32_e32 v23, v123
	global_store_dwordx4 v[36:37], v[16:19], off offset:512
	s_nop 0
	v_permlane32_swap_b32_e32 v121, v23
	v_lshlrev_b32_e32 v16, 16, v120
	v_and_b32_e32 v17, 0xffff0000, v120
	v_mul_f32_e32 v18, v24, v34
	v_mul_f32_e32 v19, v25, v34
	v_mul_f32_e32 v20, v26, v34
	v_mul_f32_e32 v21, v27, v34
	v_mul_f32_e32 v16, v18, v16
	v_mul_f32_e32 v17, v19, v17
	v_lshlrev_b32_e32 v18, 16, v121
	v_and_b32_e32 v19, 0xffff0000, v121
	v_mul_f32_e32 v18, v20, v18
	v_mul_f32_e32 v19, v21, v19
	v_cvt_pk_bf16_f32 v16, v16, v17
	v_cvt_pk_bf16_f32 v17, v18, v19
	v_lshlrev_b32_e32 v18, 16, v22
	v_and_b32_e32 v19, 0xffff0000, v22
	v_mul_f32_e32 v20, v28, v34
	v_mul_f32_e32 v21, v29, v34
	v_mul_f32_e32 v0, v0, v34
	v_mul_f32_e32 v1, v1, v34
	v_mul_f32_e32 v18, v20, v18
	v_mul_f32_e32 v19, v21, v19
	v_lshlrev_b32_e32 v20, 16, v23
	v_and_b32_e32 v21, 0xffff0000, v23
	v_mul_f32_e32 v22, v30, v34
	v_mul_f32_e32 v23, v31, v34
	v_cvt_pk_bf16_f32 v18, v18, v19
	v_mul_f32_e32 v20, v22, v20
	v_mul_f32_e32 v21, v23, v21
	s_nop 0
	v_permlane32_swap_b32_e32 v16, v18
	v_cvt_pk_bf16_f32 v19, v20, v21
	s_nop 1
	v_permlane32_swap_b32_e32 v17, v19
	global_store_dwordx4 v[36:37], v[16:19], off offset:544
	v_mul_f32_e32 v2, v2, v34
	v_mul_f32_e32 v3, v3, v34
	v_mul_f32_e32 v4, v4, v34
	v_mul_f32_e32 v5, v5, v34
	s_waitcnt vmcnt(7)
	v_mov_b32_e32 v18, v118
	s_nop 1
	v_permlane32_swap_b32_e32 v116, v18
	v_mov_b32_e32 v19, v119
	s_nop 1
	v_permlane32_swap_b32_e32 v117, v19
	v_lshlrev_b32_e32 v16, 16, v116
	v_and_b32_e32 v17, 0xffff0000, v116
	v_mul_f32_e32 v0, v0, v16
	v_mul_f32_e32 v1, v1, v17
	v_lshlrev_b32_e32 v16, 16, v117
	v_and_b32_e32 v17, 0xffff0000, v117
	v_mul_f32_e32 v2, v2, v16
	v_mul_f32_e32 v3, v3, v17
	v_cvt_pk_bf16_f32 v0, v0, v1
	v_cvt_pk_bf16_f32 v1, v2, v3
	v_lshlrev_b32_e32 v2, 16, v18
	v_and_b32_e32 v3, 0xffff0000, v18
	v_mul_f32_e32 v2, v4, v2
	v_mul_f32_e32 v3, v5, v3
	v_lshlrev_b32_e32 v4, 16, v19
	v_and_b32_e32 v5, 0xffff0000, v19
	v_mul_f32_e32 v6, v6, v34
	v_mul_f32_e32 v7, v7, v34
	v_cvt_pk_bf16_f32 v2, v2, v3
	v_mul_f32_e32 v4, v6, v4
	v_mul_f32_e32 v5, v7, v5
	s_waitcnt vmcnt(6)
	global_load_dwordx4 v[96:99], v[184:185], off offset:1024
	global_load_dwordx4 v[100:103], v[184:185], off offset:1056
	global_load_dwordx4 v[104:107], v[184:185], off offset:1088
	global_load_dwordx4 v[108:111], v[184:185], off offset:1120
	v_mov_b32_e32 v6, v114
	v_cvt_pk_bf16_f32 v3, v4, v5
	v_permlane32_swap_b32_e32 v0, v2
	s_nop 0
	v_permlane32_swap_b32_e32 v1, v3
	v_permlane32_swap_b32_e32 v112, v6
	v_mov_b32_e32 v7, v115
	global_store_dwordx4 v[36:37], v[0:3], off offset:576
	s_nop 0
	v_permlane32_swap_b32_e32 v113, v7
	v_lshlrev_b32_e32 v0, 16, v112
	v_and_b32_e32 v1, 0xffff0000, v112
	v_mul_f32_e32 v2, v8, v34
	v_mul_f32_e32 v3, v9, v34
	v_mul_f32_e32 v4, v10, v34
	v_mul_f32_e32 v5, v11, v34
	v_mul_f32_e32 v0, v2, v0
	v_mul_f32_e32 v1, v3, v1
	v_lshlrev_b32_e32 v2, 16, v113
	v_and_b32_e32 v3, 0xffff0000, v113
	v_mul_f32_e32 v2, v4, v2
	v_mul_f32_e32 v3, v5, v3
	v_cvt_pk_bf16_f32 v0, v0, v1
	v_cvt_pk_bf16_f32 v1, v2, v3
	v_lshlrev_b32_e32 v2, 16, v6
	v_and_b32_e32 v3, 0xffff0000, v6
	v_mul_f32_e32 v4, v12, v34
	v_mul_f32_e32 v5, v13, v34
	s_mov_b64 s[2:3], 0x200
	v_mul_f32_e32 v2, v4, v2
	v_mul_f32_e32 v3, v5, v3
	v_lshlrev_b32_e32 v4, 16, v7
	v_and_b32_e32 v5, 0xffff0000, v7
	v_mul_f32_e32 v6, v14, v34
	v_mul_f32_e32 v7, v15, v34
	v_cvt_pk_bf16_f32 v2, v2, v3
	v_mul_f32_e32 v4, v6, v4
	v_mul_f32_e32 v5, v7, v5
	v_lshl_add_u64 v[32:33], v[36:37], 0, s[2:3]
	v_cvt_pk_bf16_f32 v3, v4, v5
	v_permlane32_swap_b32_e32 v0, v2
	s_nop 0
	v_permlane32_swap_b32_e32 v1, v3
	s_branch .LBB0_876
